# v40 + latent HGRN pass 2: LDS read burst split so the P MFMA chain starts after the first two reads
# speedup vs baseline: 1.0002x; 1.0002x over previous
.LBB0_810:
	s_mul_i32 s10, s12, 37
	s_bfe_u32 s11, s10, 0x80008
	s_lshr_b32 s10, s10, 8
	s_sub_i32 s10, s12, s10
	s_bfe_u32 s10, s10, 0x70001
	s_add_i32 s10, s10, s11
	s_bfe_u32 s10, s10, 0x60002
	s_mul_i32 s10, s10, 7
	s_sub_i32 s10, s12, s10
	s_and_b32 s10, s10, 0xff
	s_mulk_i32 s10, 0x4400
	s_add_i32 s10, s10, 0
	v_add_u32_e32 v32, s10, v54
	v_add_u32_e32 v33, v32, v58
	ds_read2st64_b64 v[74:77], v33 offset1:8
	v_add_u32_e32 v33, v32, v59
	ds_read2st64_b64 v[78:81], v33 offset1:8
	v_add_u32_e32 v33, v32, v60
	ds_read2st64_b64 v[82:85], v33 offset1:8
	v_add_u32_e32 v33, v32, v61
	ds_read2st64_b64 v[86:89], v33 offset1:8
	v_add_u32_e32 v33, v32, v67
	ds_read2st64_b64 v[90:93], v33 offset1:8
	v_add_u32_e32 v33, v32, v69
	ds_read2st64_b64 v[94:97], v33 offset1:8
	v_add_u32_e32 v33, v32, v71
	v_add_u32_e32 v32, v32, v73
	ds_read2st64_b64 v[102:105], v32 offset1:8
	v_add_u32_e32 v32, s10, v53
	v_add3_u32 v32, v32, v56, v52
	ds_read_b64 v[62:63], v32 offset:12288
	v_add_u32_e32 v32, s10, v55
	v_add3_u32 v32, v32, v56, v52
	v_add_u32_e32 v36, s10, v57
	ds_read2st64_b64 v[98:101], v33 offset1:8
	s_waitcnt lgkmcnt(7)
	v_mov_b32_e32 v142, v76
	v_mov_b32_e32 v143, v77
	v_mov_b32_e32 v144, v80
	v_mov_b32_e32 v145, v81
	v_mov_b32_e32 v76, v78
	v_mov_b32_e32 v77, v79
	s_add_i32 s12, s16, s12
	s_and_b64 s[10:11], s[40:41], exec
	v_mfma_f32_16x16x32_bf16 v[78:81], v[142:145], v[74:77], 0
	ds_read_b128 v[106:109], v36 offset:16384
	ds_read_b128 v[110:113], v36 offset:16448
	ds_read2st64_b64 v[114:117], v32 offset0:16 offset1:17
	ds_read2st64_b64 v[118:121], v32 offset0:18 offset1:19
	ds_read_b128 v[122:125], v36 offset:16512
	ds_read_b128 v[126:129], v36 offset:16576
	ds_read_b128 v[130:133], v36 offset:16640
	ds_read_b128 v[134:137], v36 offset:16704
	ds_read2st64_b64 v[138:141], v32 offset0:20 offset1:21
	ds_read2st64_b64 v[32:35], v32 offset0:22 offset1:23
	ds_read_b128 v[40:43], v36 offset:16768
	ds_read_b128 v[36:39], v36 offset:16832
	s_waitcnt lgkmcnt(15)
	v_mov_b32_e32 v142, v84
	v_mov_b32_e32 v143, v85
	v_mov_b32_e32 v144, v88
	v_mov_b32_e32 v145, v89
	v_mov_b32_e32 v84, v86
	v_mov_b32_e32 v85, v87
	v_mov_b32_e32 v86, v92
	v_mov_b32_e32 v87, v93
	v_mov_b32_e32 v88, v96
	v_mov_b32_e32 v89, v97
	v_mfma_f32_16x16x32_bf16 v[78:81], v[142:145], v[82:85], v[78:81]
	v_mov_b32_e32 v92, v94
	v_mov_b32_e32 v93, v95
	s_cselect_b32 s10, s12, s18
	s_lshl_b32 s10, s10, 4
	v_mfma_f32_16x16x32_bf16 v[78:81], v[86:89], v[90:93], v[78:81]
	s_waitcnt lgkmcnt(12)
	v_mov_b32_e32 v86, v100
	v_mov_b32_e32 v87, v101
	v_mov_b32_e32 v88, v104
	v_mov_b32_e32 v89, v105
	v_mov_b32_e32 v100, v102
	v_mov_b32_e32 v101, v103
	s_add_i32 s10, s10, s13
	s_add_i32 s18, s18, -1
	v_mfma_f32_16x16x32_bf16 v[78:81], v[86:89], v[98:101], v[78:81]
	v_cvt_pk_bf16_f32 v86, v0, v1
	v_cvt_pk_bf16_f32 v87, v2, v3
	v_cvt_pk_bf16_f32 v88, v4, v5
	v_cvt_pk_bf16_f32 v89, v6, v7
	s_waitcnt lgkmcnt(10)
	v_pk_mul_f32 v[2:3], v[2:3], v[108:109]
	s_nop 2
	v_cndmask_b32_e64 v65, v81, 0, s[42:43]
	v_cndmask_b32_e64 v80, v80, 0, s[4:5]
	v_cndmask_b32_e64 v79, v79, 0, s[6:7]
	v_cndmask_b32_e64 v78, v78, 0, s[8:9]
	v_cvt_pk_bf16_f32 v78, v78, v79
	v_cvt_pk_bf16_f32 v79, v80, v65
	v_mov_b32_e32 v80, v64
	v_mov_b32_e32 v81, v64
	v_mov_b32_e32 v65, v64
	v_pk_mul_f32 v[0:1], v[0:1], v[106:107]
	v_pk_mul_f32 v[6:7], v[6:7], v[112:113]
	v_mfma_f32_16x16x32_bf16 v[78:81], v[78:81], v[62:65], 0
	v_mul_f32_e64 v4, v4, v110
	v_mul_f32_e64 v5, v5, v111
	s_add_i32 s12, s19, -5
	s_cmp_lg_u32 s12, 16
	v_mfma_f32_16x16x32_bf16 v[74:77], v[74:77], v[86:89], v[78:81]
	s_nop 2
	v_cvt_pk_bf16_f32 v78, v8, v9
	v_cvt_pk_bf16_f32 v79, v10, v11
	v_cvt_pk_bf16_f32 v80, v12, v13
	v_cvt_pk_bf16_f32 v81, v14, v15
	s_waitcnt lgkmcnt(7)
	v_pk_mul_f32 v[10:11], v[10:11], v[124:125]
	v_pk_mul_f32 v[8:9], v[8:9], v[122:123]
	v_mfma_f32_16x16x32_bf16 v[74:77], v[82:85], v[78:81], v[74:77]
	v_cvt_pk_bf16_f32 v78, v16, v17
	v_cvt_pk_bf16_f32 v79, v18, v19
	v_cvt_pk_bf16_f32 v80, v20, v21
	v_cvt_pk_bf16_f32 v81, v22, v23
	v_mov_b32_e32 v82, v118
	v_mov_b32_e32 v83, v119
	v_mfma_f32_16x16x32_bf16 v[74:77], v[90:93], v[78:81], v[74:77]
	v_cvt_pk_bf16_f32 v78, v24, v25
	v_cvt_pk_bf16_f32 v79, v26, v27
	v_cvt_pk_bf16_f32 v80, v28, v29
	v_cvt_pk_bf16_f32 v81, v30, v31
	v_mov_b32_e32 v84, v64
	v_mov_b32_e32 v85, v64
	v_mfma_f32_16x16x32_bf16 v[74:77], v[98:101], v[78:81], v[74:77]
	v_add_u32_e32 v78, s10, v66
	v_ashrrev_i32_e32 v79, 31, v78
	v_lshlrev_b64 v[78:79], 11, v[78:79]
	v_lshl_add_u64 v[78:79], v[50:51], 0, v[78:79]
	v_mov_b32_e32 v80, v64
	s_nop 2
	global_store_dword v[78:79], v74, off
	v_add_u32_e32 v78, s10, v68
	v_ashrrev_i32_e32 v79, 31, v78
	v_lshlrev_b64 v[78:79], 11, v[78:79]
	v_lshl_add_u64 v[78:79], v[50:51], 0, v[78:79]
	global_store_dword v[78:79], v75, off
	v_mov_b32_e32 v78, v114
	v_mov_b32_e32 v79, v115
	v_mov_b32_e32 v81, v64
	v_mfma_f32_16x16x32_bf16 v[8:11], v[82:85], v[62:65], v[8:11]
	s_waitcnt lgkmcnt(3)
	v_mov_b32_e32 v82, v138
	v_mov_b32_e32 v83, v139
	v_pk_mul_f32 v[14:15], v[14:15], v[128:129]
	v_mfma_f32_16x16x32_bf16 v[0:3], v[78:81], v[62:65], v[0:3]
	v_mov_b32_e32 v78, v116
	v_mov_b32_e32 v79, v117
	v_pk_mul_f32 v[12:13], v[12:13], v[126:127]
	v_pk_mul_f32 v[18:19], v[18:19], v[132:133]
	v_mfma_f32_16x16x32_bf16 v[4:7], v[78:81], v[62:65], v[4:7]
	v_mov_b32_e32 v78, v120
	v_mov_b32_e32 v79, v121
	v_pk_mul_f32 v[16:17], v[16:17], v[130:131]
	v_add_u32_e32 v74, s10, v70
	v_mfma_f32_16x16x32_bf16 v[12:15], v[78:81], v[62:65], v[12:15]
	v_mov_b32_e32 v78, v140
	v_mov_b32_e32 v79, v141
	v_ashrrev_i32_e32 v75, 31, v74
	v_mfma_f32_16x16x32_bf16 v[16:19], v[82:85], v[62:65], v[16:19]
	s_waitcnt lgkmcnt(0)
	v_mov_b32_e32 v82, v32
	v_mov_b32_e32 v83, v33
	v_mov_b32_e32 v32, v34
	v_mov_b32_e32 v33, v35
	v_mov_b32_e32 v34, v64
	v_mov_b32_e32 v35, v64
	v_lshlrev_b64 v[74:75], 11, v[74:75]
	v_lshl_add_u64 v[74:75], v[50:51], 0, v[74:75]
	v_pk_mul_f32 v[22:23], v[22:23], v[136:137]
	v_pk_mul_f32 v[20:21], v[20:21], v[134:135]
	v_pk_mul_f32 v[26:27], v[26:27], v[42:43]
	v_pk_mul_f32 v[24:25], v[24:25], v[40:41]
	v_pk_mul_f32 v[30:31], v[30:31], v[38:39]
	v_pk_mul_f32 v[28:29], v[28:29], v[36:37]
	global_store_dword v[74:75], v76, off
	v_add_u32_e32 v74, s10, v72
	v_mfma_f32_16x16x32_bf16 v[20:23], v[78:81], v[62:65], v[20:23]
	v_ashrrev_i32_e32 v75, 31, v74
	v_lshlrev_b64 v[74:75], 11, v[74:75]
	v_lshl_add_u64 v[74:75], v[50:51], 0, v[74:75]
	v_mfma_f32_16x16x32_bf16 v[24:27], v[82:85], v[62:65], v[24:27]
	global_store_dword v[74:75], v77, off
	v_mfma_f32_16x16x32_bf16 v[28:31], v[32:35], v[62:65], v[28:31]
	s_cbranch_scc0 .LBB0_823
